# C-attn: all 12 K fragment reads of a tile issued before the first QK MFMA (second-half reads no longer wait for the first MFMA group)
# baseline (speedup 1.0000x reference)
; template <int DQK, int VAR> ...
;     ...
;         __builtin_amdgcn_sched_barrier(0);
;         __builtin_amdgcn_s_setprio(1);
; #pragma unroll
;         for (int c = 0; c < 2; ++c) {
;             s[0][ch * 2 + c] = (f32x4){sinit, sinit, sinit, sinit}; s[1][ch * 2 + c] = s[0][ch * 2 + c];
; #pragma unroll
;             for (int ks = 0; ks < DQK / 32; ++ks) {
;                 s[0][ch * 2 + c] = __builtin_amdgcn_mfma_f32_16x16x32_bf16(kfr[c][ks], qf[0][ks], s[0][ch * 2 + c], 0, 0, 0);
;                 s[1][ch * 2 + c] = __builtin_amdgcn_mfma_f32_16x16x32_bf16(kfr[c][ks], qf[1][ks], s[1][ch * 2 + c], 0, 0, 0);
;             }
;         }
;         __builtin_amdgcn_s_setprio(0);
;         __builtin_amdgcn_sched_barrier(0);
;     }
;     __builtin_amdgcn_s_setprio(0);
;     __builtin_amdgcn_sched_barrier(0);
; #pragma unroll
;     for (int kk = 0; kk < 2; ++kk)
; #pragma unroll
;         for (int dt = 0; dt < 4; ++dt) {
;             const LAS bf16_t* vp = sVt + (dt * 16 + lr) * VP + kk * 32 + lg * 4;
;             const u32x2 v0 = *(const LAS u32x2*)vp, v1 = *(const LAS u32x2*)(vp + 16);
;             vfr[kk][dt].x = v0.x; vfr[kk][dt].y = v0.y; vfr[kk][dt].z = v1.x; vfr[kk][dt].w = v1.y;
;         }
;     __builtin_amdgcn_sched_barrier(0);
; #pragma unroll
;     for (int qt = 0; qt < 2; ++qt) {
;         const int dq = qi + qt * 16 - key0 - lg * 4;
;         const LAS float* bp = sBias + (dq + 33);
;         float ps = 0.f;
; #pragma unroll
;         for (int c = 0; c < 4; ++c)
; #pragma unroll
;             for (int j = 0; j < 4; ++j) {
;                 float val = s[qt][c][j]; float pv;
;                 if (VAR == 0) pv = fexp2(val);
;                 else if (VAR == 1) { pv = fexp2(val); pv = (dq >= c * 16 + j) ? pv : 0.f; }
;                 else if (VAR == 2) { pv = fexp2(val + bp[63 - (c * 16 + j)]); }
;                 else if (VAR == 3) { pv = fexp2(val); pv = __uint_as_float(__float_as_uint(pv) & (unsigned)__builtin_amdgcn_sbfe((int)(c < 2 ? mlo[qt] : mhi[qt]), (c & 1) * 16 + j, 1)); }
;                 else { pv = fexp2(val + bp[63 - (c * 16 + j)]); pv = __uint_as_float(__float_as_uint(pv) & (unsigned)__builtin_amdgcn_sbfe((int)(c < 2 ? mlo[qt] : mhi[qt]), (c & 1) * 16 + j, 1)); }
;                 s[qt][c][j] = pv; ps += pv;
;             }
;         lsum[qt] += ps;
;     }
;     __builtin_amdgcn_s_setprio(1);
; #pragma unroll
.LBB0_424:
	s_mulk_i32 s20, 0x6000
	s_add_i32 s20, s20, 0
	v_add_u32_e32 v70, s20, v130
	v_add_u32_e32 v161, v70, v154
	ds_read_b128 v[90:93], v161
	ds_read_b128 v[86:89], v161 offset:64
	ds_read_b128 v[82:85], v161 offset:128
	ds_read_b128 v[78:81], v161 offset:3328
	ds_read_b128 v[74:77], v161 offset:3392
	ds_read_b128 v[70:73], v161 offset:3456
	v_add3_u32 v94, s20, v153, v155
	s_cmp_gt_i32 s17, s14
	s_mov_b64 s[0:1], -1
	v_add_u32_e32 v157, 0x3800, v94
	s_cbranch_scc1 .LBB0_426
	ds_read_b128 v[110:113], v161 offset:6656
	ds_read_b128 v[114:117], v161 offset:6720
	ds_read_b128 v[118:121], v161 offset:6784
	ds_read_b128 v[122:125], v161 offset:9984
	ds_read_b128 v[162:165], v161 offset:10048
	ds_read_b128 v[166:169], v161 offset:10112
	s_setprio 1
	s_waitcnt lgkmcnt(11)
	v_mfma_f32_16x16x32_bf16 v[94:97], v[90:93], v[34:37], v[66:69]
	v_mfma_f32_16x16x32_bf16 v[98:101], v[90:93], v[46:49], v[66:69]
	s_waitcnt lgkmcnt(8)
	v_mfma_f32_16x16x32_bf16 v[102:105], v[78:81], v[34:37], v[66:69]
	v_mfma_f32_16x16x32_bf16 v[106:109], v[78:81], v[46:49], v[66:69]
	v_mfma_f32_16x16x32_bf16 v[94:97], v[86:89], v[38:41], v[94:97]
	v_mfma_f32_16x16x32_bf16 v[98:101], v[86:89], v[50:53], v[98:101]
	s_waitcnt lgkmcnt(7)
	v_mfma_f32_16x16x32_bf16 v[102:105], v[74:77], v[38:41], v[102:105]
	v_mfma_f32_16x16x32_bf16 v[106:109], v[74:77], v[50:53], v[106:109]
	v_mfma_f32_16x16x32_bf16 v[94:97], v[82:85], v[42:45], v[94:97]
	v_mfma_f32_16x16x32_bf16 v[98:101], v[82:85], v[54:57], v[98:101]
	s_waitcnt lgkmcnt(6)
	v_mfma_f32_16x16x32_bf16 v[102:105], v[70:73], v[42:45], v[102:105]
	v_mfma_f32_16x16x32_bf16 v[106:109], v[70:73], v[54:57], v[106:109]
	s_waitcnt lgkmcnt(5)
	v_mfma_f32_16x16x32_bf16 v[170:173], v[110:113], v[34:37], v[66:69]
	v_mfma_f32_16x16x32_bf16 v[110:113], v[110:113], v[46:49], v[66:69]
	s_waitcnt lgkmcnt(4)
	v_mfma_f32_16x16x32_bf16 v[170:173], v[114:117], v[38:41], v[170:173]
	v_mfma_f32_16x16x32_bf16 v[110:113], v[114:117], v[50:53], v[110:113]
	s_waitcnt lgkmcnt(3)
	v_mfma_f32_16x16x32_bf16 v[114:117], v[118:121], v[42:45], v[170:173]
	v_mfma_f32_16x16x32_bf16 v[110:113], v[118:121], v[54:57], v[110:113]
	s_waitcnt lgkmcnt(2)
	v_mfma_f32_16x16x32_bf16 v[118:121], v[122:125], v[34:37], v[66:69]
	v_mfma_f32_16x16x32_bf16 v[122:125], v[122:125], v[46:49], v[66:69]
	s_waitcnt lgkmcnt(1)
	v_mfma_f32_16x16x32_bf16 v[118:121], v[162:165], v[38:41], v[118:121]
	v_mfma_f32_16x16x32_bf16 v[122:125], v[162:165], v[50:53], v[122:125]
	s_waitcnt lgkmcnt(0)
	v_mfma_f32_16x16x32_bf16 v[118:121], v[166:169], v[42:45], v[118:121]
	v_mfma_f32_16x16x32_bf16 v[122:125], v[166:169], v[54:57], v[122:125]
	s_setprio 0
	s_setprio 0
	ds_read_b128 v[162:165], v157
	ds_read_b128 v[166:169], v157 offset:2304
	ds_read_b128 v[170:173], v157 offset:4608
	ds_read_b128 v[174:177], v157 offset:6912
	ds_read_b128 v[178:181], v157 offset:64
	ds_read_b128 v[182:185], v157 offset:2368
	ds_read_b128 v[186:189], v157 offset:4672
	ds_read_b128 v[218:221], v157 offset:6976
	v_exp_f32_e32 v191, v94
	v_exp_f32_e32 v190, v98
	v_exp_f32_e32 v201, v95
	v_exp_f32_e32 v200, v99
	v_exp_f32_e32 v215, v96
	v_exp_f32_e32 v214, v100
	v_exp_f32_e32 v223, v97
	v_exp_f32_e32 v222, v101
	v_exp_f32_e32 v225, v102
	v_exp_f32_e32 v224, v106
	v_pk_add_f32 v[94:95], v[190:191], 0 op_sel_hi:[1,0]
	v_exp_f32_e32 v231, v103
	v_exp_f32_e32 v230, v107
	v_pk_add_f32 v[94:95], v[200:201], v[94:95]
	v_exp_f32_e32 v233, v104
	v_exp_f32_e32 v232, v108
	v_pk_add_f32 v[94:95], v[214:215], v[94:95]
	v_exp_f32_e32 v235, v105
	v_exp_f32_e32 v234, v109
	v_pk_add_f32 v[94:95], v[222:223], v[94:95]
	v_exp_f32_e32 v237, v114
	v_exp_f32_e32 v236, v110
	v_pk_add_f32 v[94:95], v[94:95], v[224:225]
	v_exp_f32_e32 v239, v115
	v_pk_add_f32 v[94:95], v[230:231], v[94:95]
	v_exp_f32_e32 v238, v111
	v_exp_f32_e32 v241, v116
	v_pk_add_f32 v[94:95], v[232:233], v[94:95]
	v_exp_f32_e32 v240, v112
	v_exp_f32_e32 v243, v117
	v_pk_add_f32 v[94:95], v[234:235], v[94:95]
	v_exp_f32_e32 v242, v113
	v_exp_f32_e32 v245, v118
	v_pk_add_f32 v[94:95], v[94:95], v[236:237]
	v_exp_f32_e32 v244, v122
	v_exp_f32_e32 v247, v119
	v_exp_f32_e32 v246, v123
	v_pk_add_f32 v[94:95], v[238:239], v[94:95]
	v_exp_f32_e32 v249, v120
	v_exp_f32_e32 v248, v124
	v_pk_add_f32 v[94:95], v[240:241], v[94:95]
	v_exp_f32_e32 v203, v121
	v_pk_add_f32 v[94:95], v[242:243], v[94:95]
	v_exp_f32_e32 v202, v125
	v_pk_add_f32 v[94:95], v[94:95], v[244:245]
	s_nop 0
	v_pk_add_f32 v[94:95], v[246:247], v[94:95]
	s_nop 0
	v_pk_add_f32 v[94:95], v[248:249], v[94:95]
	s_nop 0
	v_pk_add_f32 v[144:145], v[202:203], v[94:95]
	s_setprio 1
	v_cvt_pk_bf16_f32 v94, v191, v201
	v_cvt_pk_bf16_f32 v95, v215, v223
	v_cvt_pk_bf16_f32 v96, v225, v231
	v_cvt_pk_bf16_f32 v97, v233, v235
	v_cvt_pk_bf16_f32 v98, v190, v200
	v_cvt_pk_bf16_f32 v99, v214, v222
	v_cvt_pk_bf16_f32 v100, v224, v230
	v_cvt_pk_bf16_f32 v101, v232, v234
	s_mov_b64 s[0:1], 0
	s_waitcnt lgkmcnt(7)
	v_mfma_f32_16x16x32_bf16 v[30:33], v[162:165], v[94:97], v[30:33]
	v_mfma_f32_16x16x32_bf16 v[14:17], v[162:165], v[98:101], v[14:17]
	s_waitcnt lgkmcnt(6)
	v_mfma_f32_16x16x32_bf16 v[26:29], v[166:169], v[94:97], v[26:29]
	v_mfma_f32_16x16x32_bf16 v[10:13], v[166:169], v[98:101], v[10:13]
	s_waitcnt lgkmcnt(5)
	v_mfma_f32_16x16x32_bf16 v[22:25], v[170:173], v[94:97], v[22:25]
	v_mfma_f32_16x16x32_bf16 v[6:9], v[170:173], v[98:101], v[6:9]
	v_cvt_pk_bf16_f32 v170, v237, v239
	v_cvt_pk_bf16_f32 v171, v241, v243
	v_cvt_pk_bf16_f32 v172, v245, v247
	s_waitcnt lgkmcnt(4)
	v_mfma_f32_16x16x32_bf16 v[18:21], v[174:177], v[94:97], v[18:21]
	v_cvt_pk_bf16_f32 v173, v249, v203
	v_mfma_f32_16x16x32_bf16 v[2:5], v[174:177], v[98:101], v[2:5]
	v_cvt_pk_bf16_f32 v174, v236, v238
	v_cvt_pk_bf16_f32 v175, v240, v242
	v_cvt_pk_bf16_f32 v176, v244, v246
	s_waitcnt lgkmcnt(3)
	v_mfma_f32_16x16x32_bf16 v[30:33], v[178:181], v[170:173], v[30:33]
	v_cvt_pk_bf16_f32 v177, v248, v202
	s_nop 0
	v_mfma_f32_16x16x32_bf16 v[14:17], v[178:181], v[174:177], v[14:17]
	s_waitcnt lgkmcnt(2)
	v_mfma_f32_16x16x32_bf16 v[26:29], v[182:185], v[170:173], v[26:29]
	v_mfma_f32_16x16x32_bf16 v[10:13], v[182:185], v[174:177], v[10:13]
	s_waitcnt lgkmcnt(1)
	v_mfma_f32_16x16x32_bf16 v[22:25], v[186:189], v[170:173], v[22:25]
	v_mfma_f32_16x16x32_bf16 v[6:9], v[186:189], v[174:177], v[6:9]
	s_waitcnt lgkmcnt(0)
	v_mfma_f32_16x16x32_bf16 v[18:21], v[218:221], v[170:173], v[18:21]
	v_mfma_f32_16x16x32_bf16 v[2:5], v[218:221], v[174:177], v[2:5]
